# v63 + every workgroup starts an L2 write-back (buffer_wbl2) when it arrives at a grid barrier, so the XCD leader's release fence has little left to flush
# baseline (speedup 1.0000x reference)
.LBB0_239:
	s_or_b64 exec, exec, s[6:7]
	s_waitcnt vmcnt(0)
	s_waitcnt lgkmcnt(0)
	s_barrier
	s_mov_b64 s[4:5], exec
	v_readlane_b32 s0, v254, 37
	v_readlane_b32 s1, v254, 38
	s_and_b64 s[0:1], s[4:5], s[0:1]
	s_mov_b64 exec, s[0:1]
	s_cbranch_execz .LBB0_291
	buffer_wbl2 sc1
	s_add_i32 s0, 0, 0x20160
	v_mov_b32_e32 v2, s0
	s_waitcnt vmcnt(0) expcnt(0) lgkmcnt(0)
	ds_read_b32 v4, v2
	s_add_i32 s0, 0, 0x20164
	v_mov_b32_e32 v2, s0
	ds_read_b32 v2, v2
	s_waitcnt lgkmcnt(1)
	v_cmp_ne_u32_e32 vcc, 0, v4
	s_cbranch_vccnz .LBB0_255
	v_readlane_b32 s6, v254, 0
	v_readlane_b32 s7, v254, 1
	s_load_dwordx2 s[0:1], s[6:7], 0x4
	s_add_u32 s6, s94, 0x4200
	s_addc_u32 s7, s95, 0
	s_add_u32 s20, s94, 0x4400
	s_addc_u32 s21, s95, 0
	s_add_u32 s22, s94, 0x4500
	s_addc_u32 s23, s95, 0
	s_add_u32 s24, s94, 0x4600
	s_addc_u32 s25, s95, 0
	s_add_u32 s26, s94, 0x4700
	s_addc_u32 s27, s95, 0
	s_add_u32 s28, s94, 0x4800
	s_addc_u32 s29, s95, 0
	s_add_u32 s30, s94, 0x4900
	s_addc_u32 s31, s95, 0
	s_add_u32 s34, s94, 0x4a00
	s_addc_u32 s35, s95, 0
	s_add_u32 s36, s94, 0x4b00
	s_addc_u32 s37, s95, 0
	s_add_u32 s38, s94, 0x4c00
	s_addc_u32 s39, s95, 0
	s_add_u32 s40, s94, 0x4d00
	s_addc_u32 s41, s95, 0
	s_add_u32 s42, s94, 0x4e00
	s_addc_u32 s43, s95, 0
	s_add_u32 s44, s94, 0x4f00
	s_addc_u32 s45, s95, 0
	s_add_u32 s46, s94, 0x5000
	s_addc_u32 s47, s95, 0
	s_add_u32 s48, s94, 0x5100
	s_addc_u32 s49, s95, 0
	s_add_u32 s50, s94, 0x5200
	s_addc_u32 s51, s95, 0
	s_waitcnt lgkmcnt(0)
	s_mul_i32 s0, s0, s97
	s_add_u32 s52, s94, 0x5300
	s_mul_i32 s0, s0, s1
	s_addc_u32 s53, s95, 0
	s_mov_b32 s1, 1
	v_mov_b32_e32 v18, 0
	s_branch .LBB0_243

.LBB0_549:
	s_waitcnt vmcnt(0)
	s_waitcnt vmcnt(0) lgkmcnt(0)
	s_barrier
	s_mov_b64 s[2:3], exec
	v_readlane_b32 s0, v254, 37
	v_readlane_b32 s1, v254, 38
	s_and_b64 s[0:1], s[2:3], s[0:1]
	s_mov_b64 exec, s[0:1]
	s_cbranch_execz .LBB0_601
	buffer_wbl2 sc1
	s_add_i32 s0, 0, 0x20160
	v_mov_b32_e32 v2, s0
	s_waitcnt vmcnt(0) expcnt(0) lgkmcnt(0)
	ds_read_b32 v4, v2
	s_add_i32 s0, 0, 0x20164
	v_mov_b32_e32 v2, s0
	ds_read_b32 v2, v2
	s_waitcnt lgkmcnt(1)
	v_cmp_ne_u32_e32 vcc, 0, v4
	s_cbranch_vccnz .LBB0_565
	v_readlane_b32 s4, v254, 0
	v_readlane_b32 s5, v254, 1
	s_load_dwordx2 s[0:1], s[4:5], 0x4
	s_add_u32 s4, s94, 0x4200
	s_addc_u32 s5, s95, 0
	s_add_u32 s6, s94, 0x4400
	s_addc_u32 s7, s95, 0
	s_add_u32 s16, s94, 0x4500
	s_addc_u32 s17, s95, 0
	s_add_u32 s18, s94, 0x4600
	s_addc_u32 s19, s95, 0
	s_add_u32 s20, s94, 0x4700
	s_addc_u32 s21, s95, 0
	s_add_u32 s22, s94, 0x4800
	s_addc_u32 s23, s95, 0
	s_add_u32 s24, s94, 0x4900
	s_addc_u32 s25, s95, 0
	s_add_u32 s26, s94, 0x4a00
	s_addc_u32 s27, s95, 0
	s_add_u32 s28, s94, 0x4b00
	s_addc_u32 s29, s95, 0
	s_add_u32 s30, s94, 0x4c00
	s_addc_u32 s31, s95, 0
	s_add_u32 s34, s94, 0x4d00
	s_addc_u32 s35, s95, 0
	s_add_u32 s36, s94, 0x4e00
	s_addc_u32 s37, s95, 0
	s_add_u32 s38, s94, 0x4f00
	s_addc_u32 s39, s95, 0
	s_add_u32 s40, s94, 0x5000
	s_addc_u32 s41, s95, 0
	s_add_u32 s42, s94, 0x5100
	s_addc_u32 s43, s95, 0
	s_add_u32 s44, s94, 0x5200
	s_addc_u32 s45, s95, 0
	s_waitcnt lgkmcnt(0)
	s_mul_i32 s0, s0, s97
	s_add_u32 s46, s94, 0x5300
	s_mul_i32 s0, s0, s1
	s_addc_u32 s47, s95, 0
	s_mov_b32 s1, 1
	v_mov_b32_e32 v18, 0
	s_branch .LBB0_553

.LBB0_671:
	s_waitcnt vmcnt(0)
	s_barrier
	s_mov_b64 s[2:3], exec
	v_readlane_b32 s0, v254, 37
	v_readlane_b32 s1, v254, 38
	s_and_b64 s[0:1], s[2:3], s[0:1]
	s_mov_b64 exec, s[0:1]
	s_cbranch_execz .LBB0_723
	buffer_wbl2 sc1
	s_add_i32 s0, 0, 0x20160
	v_mov_b32_e32 v2, s0
	s_waitcnt vmcnt(0) expcnt(0) lgkmcnt(0)
	ds_read_b32 v4, v2
	s_add_i32 s0, 0, 0x20164
	v_mov_b32_e32 v2, s0
	ds_read_b32 v2, v2
	s_waitcnt lgkmcnt(1)
	v_cmp_ne_u32_e32 vcc, 0, v4
	s_cbranch_vccnz .LBB0_687
	v_readlane_b32 s4, v254, 0
	v_readlane_b32 s5, v254, 1
	s_load_dwordx2 s[0:1], s[4:5], 0x4
	s_add_u32 s4, s94, 0x4200
	s_addc_u32 s5, s95, 0
	s_add_u32 s6, s94, 0x4400
	s_addc_u32 s7, s95, 0
	s_add_u32 s8, s94, 0x4500
	s_addc_u32 s9, s95, 0
	s_add_u32 s12, s94, 0x4600
	s_addc_u32 s13, s95, 0
	s_add_u32 s16, s94, 0x4700
	s_addc_u32 s17, s95, 0
	s_add_u32 s18, s94, 0x4800
	s_addc_u32 s19, s95, 0
	s_add_u32 s20, s94, 0x4900
	s_addc_u32 s21, s95, 0
	s_add_u32 s22, s94, 0x4a00
	s_addc_u32 s23, s95, 0
	s_add_u32 s24, s94, 0x4b00
	s_addc_u32 s25, s95, 0
	s_add_u32 s26, s94, 0x4c00
	s_addc_u32 s27, s95, 0
	s_add_u32 s28, s94, 0x4d00
	s_addc_u32 s29, s95, 0
	s_add_u32 s30, s94, 0x4e00
	s_addc_u32 s31, s95, 0
	s_add_u32 s34, s94, 0x4f00
	s_addc_u32 s35, s95, 0
	s_add_u32 s36, s94, 0x5000
	s_addc_u32 s37, s95, 0
	s_add_u32 s38, s94, 0x5100
	s_addc_u32 s39, s95, 0
	s_add_u32 s40, s94, 0x5200
	s_addc_u32 s41, s95, 0
	s_waitcnt lgkmcnt(0)
	s_mul_i32 s0, s0, s97
	s_add_u32 s42, s94, 0x5300
	s_mul_i32 s0, s0, s1
	s_addc_u32 s43, s95, 0
	s_mov_b32 s1, 1
	v_mov_b32_e32 v18, 0
	s_branch .LBB0_675

.LBB0_759:
	s_waitcnt vmcnt(0)
	s_barrier
	s_mov_b64 s[2:3], exec
	v_readlane_b32 s0, v254, 37
	v_readlane_b32 s1, v254, 38
	s_and_b64 s[0:1], s[2:3], s[0:1]
	s_mov_b64 exec, s[0:1]
	s_cbranch_execz .LBB0_811
	buffer_wbl2 sc1
	s_add_i32 s0, 0, 0x20160
	v_mov_b32_e32 v2, s0
	s_waitcnt vmcnt(0) expcnt(0) lgkmcnt(0)
	ds_read_b32 v4, v2
	s_add_i32 s0, 0, 0x20164
	v_mov_b32_e32 v2, s0
	ds_read_b32 v2, v2
	s_waitcnt lgkmcnt(1)
	v_cmp_ne_u32_e32 vcc, 0, v4
	s_cbranch_vccnz .LBB0_775
	v_readlane_b32 s4, v254, 0
	v_readlane_b32 s5, v254, 1
	s_load_dwordx2 s[0:1], s[4:5], 0x4
	s_add_u32 s4, s94, 0x4200
	s_addc_u32 s5, s95, 0
	s_add_u32 s6, s94, 0x4400
	s_addc_u32 s7, s95, 0
	s_add_u32 s8, s94, 0x4500
	s_addc_u32 s9, s95, 0
	s_add_u32 s16, s94, 0x4600
	s_addc_u32 s17, s95, 0
	s_add_u32 s18, s94, 0x4700
	s_addc_u32 s19, s95, 0
	s_add_u32 s20, s94, 0x4800
	s_addc_u32 s21, s95, 0
	s_add_u32 s22, s94, 0x4900
	s_addc_u32 s23, s95, 0
	s_add_u32 s24, s94, 0x4a00
	s_addc_u32 s25, s95, 0
	s_add_u32 s26, s94, 0x4b00
	s_addc_u32 s27, s95, 0
	s_add_u32 s28, s94, 0x4c00
	s_addc_u32 s29, s95, 0
	s_add_u32 s30, s94, 0x4d00
	s_addc_u32 s31, s95, 0
	s_add_u32 s34, s94, 0x4e00
	s_addc_u32 s35, s95, 0
	s_add_u32 s36, s94, 0x4f00
	s_addc_u32 s37, s95, 0
	s_add_u32 s38, s94, 0x5000
	s_addc_u32 s39, s95, 0
	s_add_u32 s40, s94, 0x5100
	s_addc_u32 s41, s95, 0
	s_add_u32 s42, s94, 0x5200
	s_addc_u32 s43, s95, 0
	s_waitcnt lgkmcnt(0)
	s_mul_i32 s0, s0, s97
	s_add_u32 s44, s94, 0x5300
	s_mul_i32 s0, s0, s1
	s_addc_u32 s45, s95, 0
	s_mov_b32 s1, 1
	v_mov_b32_e32 v18, 0
	s_branch .LBB0_763

.LBB0_900:
	s_waitcnt vmcnt(0)
	s_barrier
	s_waitcnt vmcnt(0)
	s_barrier
	s_mov_b64 s[2:3], exec
	v_readlane_b32 s0, v254, 37
	v_readlane_b32 s36, v254, 18
	v_readlane_b32 s1, v254, 38
	v_readlane_b32 s50, v254, 32
	v_readlane_b32 s51, v254, 33
	v_readlane_b32 s52, v254, 62
	v_readlane_b32 s60, v253, 8
	s_and_b64 s[0:1], s[2:3], s[0:1]
	s_mov_b64 s[62:63], s[50:51]
	v_readlane_b32 s53, v254, 63
	v_readlane_b32 s61, v253, 9
	v_readlane_b32 s37, v254, 19
	v_readlane_b32 s38, v254, 20
	v_readlane_b32 s39, v254, 21
	v_readlane_b32 s40, v254, 22
	v_readlane_b32 s41, v254, 23
	v_readlane_b32 s42, v254, 24
	v_readlane_b32 s43, v254, 25
	v_readlane_b32 s44, v254, 26
	v_readlane_b32 s45, v254, 27
	v_readlane_b32 s46, v254, 28
	v_readlane_b32 s47, v254, 29
	v_readlane_b32 s48, v254, 30
	v_readlane_b32 s49, v254, 31
	s_mov_b64 exec, s[0:1]
	s_cbranch_execz .LBB0_952
	buffer_wbl2 sc1
	s_add_i32 s0, 0, 0x20160
	v_mov_b32_e32 v2, s0
	s_waitcnt vmcnt(0) expcnt(0) lgkmcnt(0)
	ds_read_b32 v4, v2
	s_add_i32 s0, 0, 0x20164
	v_mov_b32_e32 v2, s0
	ds_read_b32 v2, v2
	s_waitcnt lgkmcnt(1)
	v_cmp_ne_u32_e32 vcc, 0, v4
	s_cbranch_vccnz .LBB0_916
	v_readlane_b32 s4, v254, 0
	v_readlane_b32 s5, v254, 1
	s_load_dwordx2 s[0:1], s[4:5], 0x4
	s_add_u32 s4, s94, 0x4200
	s_addc_u32 s5, s95, 0
	s_add_u32 s6, s94, 0x4400
	s_addc_u32 s7, s95, 0
	s_add_u32 s8, s94, 0x4500
	s_addc_u32 s9, s95, 0
	s_add_u32 s14, s94, 0x4600
	s_addc_u32 s15, s95, 0
	s_add_u32 s18, s94, 0x4700
	s_addc_u32 s19, s95, 0
	s_add_u32 s20, s94, 0x4800
	s_addc_u32 s21, s95, 0
	s_add_u32 s22, s94, 0x4900
	s_addc_u32 s23, s95, 0
	s_add_u32 s24, s94, 0x4a00
	s_addc_u32 s25, s95, 0
	s_add_u32 s26, s94, 0x4b00
	s_addc_u32 s27, s95, 0
	s_add_u32 s28, s94, 0x4c00
	s_addc_u32 s29, s95, 0
	s_add_u32 s30, s94, 0x4d00
	s_addc_u32 s31, s95, 0
	s_add_u32 s34, s94, 0x4e00
	s_addc_u32 s35, s95, 0
	s_add_u32 s36, s94, 0x4f00
	s_addc_u32 s37, s95, 0
	s_add_u32 s38, s94, 0x5000
	s_addc_u32 s39, s95, 0
	s_add_u32 s40, s94, 0x5100
	s_addc_u32 s41, s95, 0
	s_add_u32 s42, s94, 0x5200
	s_addc_u32 s43, s95, 0
	s_waitcnt lgkmcnt(0)
	s_mul_i32 s0, s0, s97
	s_add_u32 s44, s94, 0x5300
	s_mul_i32 s0, s0, s1
	s_addc_u32 s45, s95, 0
	s_mov_b32 s1, 1
	v_mov_b32_e32 v18, 0
	s_branch .LBB0_904

.LBB0_995:
	s_waitcnt vmcnt(0)
	s_waitcnt vmcnt(0)
	s_barrier
	s_mov_b64 s[0:1], exec
	v_readlane_b32 s2, v254, 37
	v_readlane_b32 s3, v254, 38
	s_and_b64 s[2:3], s[0:1], s[2:3]
	s_mov_b64 exec, s[2:3]
	s_cbranch_execz .LBB0_1047
	buffer_wbl2 sc1
	s_add_i32 s2, 0, 0x20160
	v_mov_b32_e32 v1, s2
	s_waitcnt vmcnt(0) expcnt(0) lgkmcnt(0)
	ds_read_b32 v3, v1
	s_add_i32 s2, 0, 0x20164
	v_mov_b32_e32 v1, s2
	ds_read_b32 v1, v1
	s_waitcnt lgkmcnt(1)
	v_cmp_ne_u32_e32 vcc, 0, v3
	s_cbranch_vccnz .LBB0_1011
	v_readlane_b32 s2, v254, 0
	v_readlane_b32 s3, v254, 1
	s_load_dwordx2 s[6:7], s[2:3], 0x4
	s_add_u32 s2, s94, 0x4200
	s_addc_u32 s3, s95, 0
	s_add_u32 s4, s94, 0x4400
	s_addc_u32 s5, s95, 0
	s_waitcnt lgkmcnt(0)
	s_mul_i32 s33, s6, s97
	s_add_u32 s6, s94, 0x4500
	s_mul_i32 s33, s33, s7
	s_addc_u32 s7, s95, 0
	s_add_u32 s8, s94, 0x4600
	s_addc_u32 s9, s95, 0
	s_add_u32 s14, s94, 0x4700
	s_addc_u32 s15, s95, 0
	s_add_u32 s18, s94, 0x4800
	s_addc_u32 s19, s95, 0
	s_add_u32 s20, s94, 0x4900
	s_addc_u32 s21, s95, 0
	s_add_u32 s22, s94, 0x4a00
	s_addc_u32 s23, s95, 0
	s_add_u32 s24, s94, 0x4b00
	s_addc_u32 s25, s95, 0
	s_add_u32 s26, s94, 0x4c00
	s_addc_u32 s27, s95, 0
	s_add_u32 s28, s94, 0x4d00
	s_addc_u32 s29, s95, 0
	s_add_u32 s30, s94, 0x4e00
	s_addc_u32 s31, s95, 0
	s_add_u32 s34, s94, 0x4f00
	s_addc_u32 s35, s95, 0
	s_add_u32 s36, s94, 0x5000
	s_addc_u32 s37, s95, 0
	s_add_u32 s38, s94, 0x5100
	s_addc_u32 s39, s95, 0
	s_add_u32 s40, s94, 0x5200
	s_addc_u32 s41, s95, 0
	s_add_u32 s42, s94, 0x5300
	s_addc_u32 s43, s95, 0
	s_mov_b32 s50, 1
	v_mov_b32_e32 v17, 0
	s_branch .LBB0_999
